# mLSTM chunk loop: hand-scheduled body (all LDS reads issued early) + V/VW image row pitch 112->96 B (transposed reads bank-conflict free)
# baseline (speedup 1.0000x reference)
.LBB0_208:
	s_add_u32 s0, s10, 0xac00000
	s_addc_u32 s1, s11, 0
	v_writelane_b32 v254, s0, 50
	s_cmp_gt_i32 s82, 1
	s_mov_b64 s[26:27], -1
	v_writelane_b32 v254, s1, 51
	s_cbranch_scc0 .LBB0_280
	v_writelane_b32 v254, s56, 52
	v_readlane_b32 s0, v253, 12
	v_mov_b32_e32 v56, v167
	v_writelane_b32 v254, s57, 53
	v_writelane_b32 v254, s86, 54
	v_writelane_b32 v254, s82, 55
	v_readlane_b32 s1, v253, 13
	s_movk_i32 s17, 0x1fff
	v_writelane_b32 v254, s83, 56
	s_andn2_b64 vcc, exec, s[0:1]
	v_readfirstlane_b32 s4, v56
	s_cbranch_vccnz .LBB0_279
	s_ashr_i32 s6, s4, 6
	s_add_u32 s0, s10, 0x1b400000
	v_and_b32_e32 v81, 63, v56
	v_writelane_b32 v254, s0, 57
	s_addc_u32 s0, s11, 0
	s_ashr_i32 s1, s4, 8
	s_and_b32 s7, s6, 3
	s_cmp_lt_u32 s4, 64
	v_lshlrev_b32_e32 v58, 2, v81
	s_cselect_b64 s[20:21], -1, 0
	v_or_b32_e32 v0, 0x100, v58
	s_add_i32 s16, 0, 0x14200
	v_writelane_b32 v254, s0, 58
	v_add_u32_e32 v91, s16, v58
	v_add_u32_e32 v92, s16, v0
	s_add_i32 s16, 0, 0x14400
	v_writelane_b32 v254, s20, 59
	v_add_u32_e32 v93, s16, v58
	v_add_u32_e32 v94, s16, v0
	s_add_i32 s16, 0, 0x14600
	v_writelane_b32 v254, s21, 60
	v_add_u32_e32 v95, s16, v58
	v_add_u32_e32 v96, s16, v0
	s_add_i32 s16, 0, 0x14800
	v_add_u32_e32 v97, s16, v58
	v_writelane_b32 v254, s16, 61
	v_add_u32_e32 v98, s16, v0
	s_movk_i32 s16, 0xff
	v_cmp_lt_i32_e64 s[42:43], s16, v56
	s_movk_i32 s16, 0x100
	v_ashrrev_i32_e32 v83, 3, v56
	v_and_b32_e32 v4, 7, v56
	s_add_i32 s0, 0, 0x14000
	v_cmp_gt_i32_e64 s[44:45], s16, v56
	s_movk_i32 s16, 0x140
	s_movk_i32 s20, 0x90
	v_add_u32_e32 v90, s0, v0
	v_lshlrev_b32_e32 v0, 3, v4
	v_add_u32_e32 v10, 0xffffff00, v56
	v_cmp_gt_i32_e64 s[46:47], s16, v56
	v_mul_lo_u32 v11, v83, s20
	v_lshlrev_b32_e32 v4, 4, v4
	s_movk_i32 s16, 0x60
	v_lshrrev_b32_e32 v2, 2, v56
	v_add3_u32 v101, 0, v11, v4
	v_mul_lo_u32 v4, v10, s16
	s_movk_i32 s16, 0x360
	v_bitop3_b32 v100, v2, s17, 63 bitop3:0x6c
	v_cmp_gt_i32_e64 s[16:17], s16, v56
	v_bfe_u32 v86, v56, 2, 6
	s_waitcnt lgkmcnt(0)
	v_and_b32_e32 v3, 3, v56
	v_writelane_b32 v254, s16, 62
	v_and_b32_e32 v6, 15, v56
	v_lshlrev_b32_e32 v2, 3, v3
	v_writelane_b32 v254, s17, 63
	s_lshl_b32 s16, s7, 4
	v_add_u32_e32 v102, 0, v4
	v_mul_u32_u24_e32 v4, 0x60, v86
	v_lshlrev_b32_e32 v3, 4, v3
	v_or_b32_e32 v105, s16, v6
	s_lshl_b32 s28, s1, 4
	v_add3_u32 v103, 0, v4, v3
	s_ashr_i32 s29, s28, 31
	v_lshl_add_u32 v107, v105, 2, 0
	v_mul_u32_u24_e32 v4, 0x8c, v105
	v_and_b32_e32 v108, 48, v56
	s_lshl_b32 s7, s7, 5
	v_add3_u32 v109, v107, v4, v108
	v_or_b32_e32 v4, s28, v6
	s_cmp_lg_u32 0, -1
	v_mov_b32_e32 v3, 0x1fff
	v_mul_lo_u32 v110, v4, s20
	v_bfe_u32 v4, v56, 2, 2
	v_lshlrev_b32_e32 v11, 3, v56
	s_cselect_b32 s17, 0, 0
	v_bfe_u32 v5, v56, 4, 2
	v_cndmask_b32_e64 v60, v10, v86, s[44:45]
	v_bitop3_b32 v106, s16, v3, v6 bitop3:0x36
	v_mul_u32_u24_e32 v10, 0x60, v4
	v_and_b32_e32 v11, 24, v11
	v_mul_u32_u24_e32 v4, 0x90, v4
	s_add_i32 s16, s17, 0x4800
	v_mul_u32_u24_e32 v112, 0x240, v5
	v_add3_u32 v4, v11, s16, v4
	v_add3_u32 v113, v4, v112, s7
	v_mul_u32_u24_e32 v4, 0x180, v5
	v_and_b32_e32 v8, 64, v212
	v_add3_u32 v4, v10, v11, v4
	v_add_u32_e32 v11, -1, v212
	v_cmp_lt_i32_e32 vcc, v11, v8
	v_add_u32_e32 v9, 64, v8
	v_lshlrev_b32_e32 v3, 2, v5
	v_cndmask_b32_e32 v11, v11, v212, vcc
	v_lshlrev_b32_e32 v117, 2, v11
	v_add_u32_e32 v11, -2, v212
	v_cmp_lt_i32_e32 vcc, v11, v8
	s_lshl_b32 s27, s1, 5
	s_add_i32 s7, s17, 0xd200
	v_cndmask_b32_e32 v11, v11, v212, vcc
	v_lshlrev_b32_e32 v118, 2, v11
	v_add_u32_e32 v11, -4, v212
	v_cmp_lt_i32_e32 vcc, v11, v8
	s_add_i32 s48, s27, 0x600
	s_add_i32 s49, s27, 0xc00
	v_cndmask_b32_e32 v11, v11, v212, vcc
	v_lshlrev_b32_e32 v119, 2, v11
	v_add_u32_e32 v11, -8, v212
	v_cmp_lt_i32_e32 vcc, v11, v8
	s_add_i32 s26, s27, 0x1200
	s_cmpk_gt_u32 s4, 0xff
	v_cndmask_b32_e32 v11, v11, v212, vcc
	v_lshlrev_b32_e32 v120, 2, v11
	v_add_u32_e32 v11, -16, v212
	v_cmp_lt_i32_e32 vcc, v11, v8
	s_cselect_b64 s[36:37], -1, 0
	s_add_i32 s1, s17, 0x9000
	v_cndmask_b32_e32 v11, v11, v212, vcc
	v_lshlrev_b32_e32 v121, 2, v11
	v_subrev_u32_e32 v11, 32, v212
	v_cmp_lt_i32_e32 vcc, v11, v8
	v_add_u32_e32 v116, s1, v4
	s_add_i32 s1, 0, 0x12500
	v_cndmask_b32_e32 v11, v11, v212, vcc
	v_lshlrev_b32_e32 v122, 2, v11
	v_xor_b32_e32 v11, 32, v212
	v_cmp_lt_i32_e32 vcc, v11, v9
	v_mov_b32_e32 v12, s1
	s_andn2_b32 s4, s4, 63
	v_cndmask_b32_e32 v11, v212, v11, vcc
	v_lshlrev_b32_e32 v123, 2, v11
	v_xor_b32_e32 v11, 16, v212
	v_cmp_lt_i32_e32 vcc, v11, v9
	v_or_b32_e32 v10, s28, v3
	v_writelane_b32 v255, s4, 0
	v_cndmask_b32_e32 v11, v212, v11, vcc
	v_lshlrev_b32_e32 v124, 2, v11
	v_xor_b32_e32 v11, 8, v212
	v_cmp_lt_i32_e32 vcc, v11, v9
	s_sub_i32 s4, 0x1fc0, s4
	s_add_i32 s16, 0, 0x10a00
	v_cndmask_b32_e32 v11, v212, v11, vcc
	v_lshlrev_b32_e32 v125, 2, v11
	v_xor_b32_e32 v11, 4, v212
	v_cmp_lt_i32_e32 vcc, v11, v9
	v_writelane_b32 v255, s4, 1
	s_mul_hi_i32 s4, s6, 0x500
	v_cndmask_b32_e32 v11, v212, v11, vcc
	v_lshlrev_b32_e32 v126, 2, v11
	v_xor_b32_e32 v11, 2, v212
	v_cmp_lt_i32_e32 vcc, v11, v9
	v_mul_lo_u32 v129, v10, s20
	v_cmp_gt_u32_e64 s[60:61], v3, v105
	v_cndmask_b32_e32 v11, v212, v11, vcc
	v_lshlrev_b32_e32 v127, 2, v11
	v_xor_b32_e32 v11, 1, v212
	v_cmp_lt_i32_e32 vcc, v11, v9
	v_cmp_lt_u32_e64 s[62:63], v3, v105
	v_or_b32_e32 v10, 2, v3
	v_cndmask_b32_e32 v9, v212, v11, vcc
	v_or_b32_e32 v11, 16, v3
	v_cmp_gt_u32_e64 s[66:67], v11, v105
	v_or_b32_e32 v11, 17, v3
	v_cmp_gt_u32_e64 s[68:69], v11, v105
	v_or_b32_e32 v11, 18, v3
	v_cmp_gt_u32_e64 s[70:71], v11, v105
	v_or_b32_e32 v11, 19, v3
	v_cmp_gt_u32_e64 s[72:73], v11, v105
	v_or_b32_e32 v11, 32, v3
	v_cmp_gt_u32_e64 s[74:75], v11, v105
	v_or_b32_e32 v11, 33, v3
	v_cmp_gt_u32_e64 s[76:77], v11, v105
	v_or_b32_e32 v11, 34, v3
	v_cmp_gt_u32_e64 s[78:79], v11, v105
	v_or_b32_e32 v11, 35, v3
	v_cmp_gt_u32_e64 s[80:81], v11, v105
	v_or_b32_e32 v11, 48, v3
	v_cmp_gt_u32_e64 s[82:83], v11, v105
	v_or_b32_e32 v11, 49, v3
	v_cmp_gt_u32_e64 s[84:85], v11, v105
	v_or_b32_e32 v11, 50, v3
	v_cmp_gt_u32_e64 s[86:87], v11, v105
	v_add_u32_e32 v11, s1, v110
	s_add_i32 s1, s17, 0xee00
	v_add_u32_e32 v13, s1, v4
	s_add_i32 s1, s17, 0xee40
	v_add_u32_e32 v131, s1, v4
	s_add_i32 s1, s17, 0xf440
	v_add_u32_e32 v132, s1, v4
	s_add_i32 s1, s17, 0xfa40
	v_add_u32_e32 v133, s1, v4
	s_add_i32 s1, s17, 0x10040
	v_add_u32_e32 v134, s1, v4
	s_add_i32 s1, s17, 0xac00
	v_add_u32_e32 v14, s1, v4
	s_add_i32 s1, s17, 0xac40
	v_add_u32_e32 v135, s1, v4
	s_add_i32 s1, s17, 0xb240
	v_add_u32_e32 v136, s1, v4
	s_add_i32 s1, s17, 0xb840
	v_add_u32_e32 v137, s1, v4
	s_add_i32 s17, s17, 0xbe40
	s_lshl_b32 s1, s6, 2
	v_add_u32_e32 v138, s17, v4
	s_add_i32 s17, s1, 0
	s_mulk_i32 s6, 0x500
	v_lshlrev_b32_e32 v128, 2, v9
	v_or_b32_e32 v9, 3, v3
	v_or_b32_e32 v3, 51, v3
	s_add_u32 s6, s10, s6
	v_add_u32_e32 v114, s7, v4
	s_addc_u32 s7, s11, s4
	v_cmp_gt_u32_e64 s[88:89], v3, v105
	v_or_b32_e32 v3, v8, v6
	v_mov_b32_e32 v59, v1
	v_mul_u32_u24_e32 v111, 0x90, v6
	v_lshlrev_b32_e32 v115, 1, v105
	v_lshlrev_b32_e32 v139, 2, v3
	v_mad_u32_u24 v3, v6, s20, v12
	v_mov_b32_e32 v6, s16
	s_movk_i32 s4, 0x240
	v_lshl_add_u64 v[62:63], s[6:7], 0, v[58:59]
	s_mov_b64 s[6:7], 0x1b402c00
	v_lshlrev_b32_e32 v7, 2, v212
	v_add_u32_e32 v89, s0, v58
	v_cmp_gt_u32_e64 s[64:65], v10, v105
	v_add_u32_e32 v4, s16, v115
	v_mad_u32_u24 v8, v5, s4, v6
	v_mad_u32_u24 v10, v10, s20, v6
	v_mad_u32_u24 v6, v9, s20, v6
	v_lshl_add_u64 v[64:65], v[62:63], 0, s[6:7]
	s_add_i32 s0, s0, s1
	s_lshl_b64 s[6:7], s[28:29], 1
	v_bitop3_b32 v87, v56, 63, v56 bitop3:0xc
	v_or_b32_e32 v88, 0xfc, v7
	v_cmp_eq_u32_e64 s[40:41], 0, v81
	v_sub_u32_e32 v99, 0x1fff, v83
	v_ashrrev_i32_e32 v57, 31, v56
	v_ashrrev_i32_e32 v61, 31, v60
	v_lshl_add_u32 v104, v56, 2, 0
	v_cmp_gt_u32_e64 s[50:51], 2, v81
	v_cmp_gt_u32_e64 s[52:53], 4, v81
	v_cmp_gt_u32_e64 s[54:55], 8, v81
	v_cmp_gt_u32_e64 s[56:57], 16, v81
	v_cmp_gt_u32_e64 s[58:59], 32, v81
	v_mul_u32_u24_e32 v130, 0x90, v9
	v_add_u32_e32 v140, 0x2400, v113
	v_add_u32_e32 v141, 0x3600, v113
	v_add_u32_e32 v142, 0x2d00, v113
	v_add_u32_e32 v143, 0x3f00, v113
	v_add_u32_e32 v144, s27, v13
	v_add_u32_e32 v145, s48, v13
	v_add_u32_e32 v146, s49, v13
	v_add_u32_e32 v147, s26, v13
	v_add3_u32 v148, 0, v108, v111
	v_add_u32_e32 v149, s27, v14
	v_add_u32_e32 v150, s48, v14
	v_add_u32_e32 v151, s49, v14
	v_add_u32_e32 v152, s26, v14
	v_cmp_gt_u32_e64 s[90:91], v9, v105
	v_and_b32_e32 v59, 0x100, v7
	v_writelane_b32 v255, s0, 2
	v_add_u32_e32 v153, 0xfffffe00, v56
	v_lshl_add_u32 v154, v56, 4, s16
	v_lshl_or_b32 v66, v5, 3, s6
	v_mov_b32_e32 v67, s7
	v_lshlrev_b32_e32 v68, 1, v0
	v_lshlrev_b32_e32 v70, 1, v2
	v_add_u32_e32 v155, v11, v108
	v_add_u32_e32 v156, v3, v108
	v_add_u32_e32 v157, v8, v115
	v_add_u32_e32 v158, v10, v115
	v_add_u32_e32 v159, v6, v115
	v_add_u32_e32 v160, v4, v129
	v_readlane_b32 s33, v253, 30
	v_readlane_b32 s6, v253, 27
	v_readlane_b32 s7, v253, 29
	s_branch .LBB0_212

.LBB0_252:
	s_and_b32 s0, s4, 1
	s_mul_i32 s23, s0, 0x2400
	s_mul_i32 s1, s0, 0x1b00
	s_mul_i32 s22, s0, 0x1c00
	s_mul_i32 s30, s0, 0x500
	s_xor_b32 s21, s0, 1
	s_add_i32 s1, s16, s1
	s_mul_i32 s34, s21, 0x1b00
	v_add_u32_e32 v168, s23, v109
	v_add_u32_e32 v169, s23, v148
	s_add_i32 s34, s16, s34
	ds_read_b128 v[40:43], v168
	ds_read_b128 v[44:47], v168 offset:64
	ds_read_b128 v[48:51], v169 offset:18432
	ds_read_b128 v[52:55], v169 offset:18496
	ds_read_b128 v[180:183], v169 offset:20736
	ds_read_b128 v[184:187], v169 offset:20800
	ds_read_b128 v[188:191], v169 offset:23040
	ds_read_b128 v[192:195], v169 offset:23104
	ds_read_b128 v[36:39], v169 offset:25344
	ds_read_b128 v[196:199], v169 offset:25408
	v_add3_u32 v179, s1, v110, v108
	v_add3_u32 v208, s1, v111, v108
	ds_read_b128 v[230:233], v179
	ds_read_b128 v[234:237], v179 offset:64
	ds_read_b128 v[238:241], v208 offset:4608
	ds_read_b128 v[242:245], v208 offset:4672
	v_add_u32_e32 v209, s22, v116
	v_add_u32_e32 v0, s30, v107
	v_add_u32_e32 v220, s27, v209
	v_mov_b32_e32 v250, s20
	s_mov_b64 s[92:93], 0
	s_waitcnt lgkmcnt(11)
	v_mfma_f32_16x16x32_bf16 v[48:51], v[48:51], v[40:43], 0
	ds_read_b64_tr_b16 v[200:201], v220
	s_waitcnt lgkmcnt(11)
	v_mfma_f32_16x16x32_bf16 v[48:51], v[52:55], v[44:47], v[48:51]
	ds_read_b64_tr_b16 v[202:203], v220 offset:1536
	s_waitcnt lgkmcnt(11)
	v_mfma_f32_16x16x32_bf16 v[180:183], v[180:183], v[40:43], 0
	ds_read_b64_tr_b16 v[204:205], v209 offset:64
	s_waitcnt lgkmcnt(11)
	v_mfma_f32_16x16x32_bf16 v[180:183], v[184:187], v[44:47], v[180:183]
	ds_read_b64_tr_b16 v[206:207], v209 offset:1600
	s_waitcnt lgkmcnt(11)
	v_mfma_f32_16x16x32_bf16 v[188:191], v[188:191], v[40:43], 0
	ds_read_b64_tr_b16 v[246:247], v220 offset:3072
	s_waitcnt lgkmcnt(11)
	v_mfma_f32_16x16x32_bf16 v[188:191], v[192:195], v[44:47], v[188:191]
	ds_read_b64_tr_b16 v[248:249], v220 offset:4608
	s_waitcnt lgkmcnt(11)
	v_mfma_f32_16x16x32_bf16 v[36:39], v[36:39], v[40:43], 0
	ds_read_b64_tr_b16 v[216:217], v209 offset:3136
	s_waitcnt lgkmcnt(11)
	v_mfma_f32_16x16x32_bf16 v[36:39], v[196:199], v[44:47], v[36:39]
	ds_read_b64_tr_b16 v[218:219], v209 offset:4672
	s_waitcnt lgkmcnt(11)
	v_mfma_f32_16x16x32_bf16 v[230:233], v[230:233], v[40:43], 0
	ds_read2st64_b32 v[2:3], v0 offset0:200 offset1:201
	s_waitcnt lgkmcnt(11)
	v_mfma_f32_16x16x32_bf16 v[230:233], v[234:237], v[44:47], v[230:233]
	ds_read_b32 v0, v0 offset:51712
	s_waitcnt lgkmcnt(11)
	v_mfma_f32_16x16x32_bf16 v[238:241], v[238:241], v[40:43], 0
	ds_read_b32 v176, v250
	s_waitcnt lgkmcnt(11)
	v_mfma_f32_16x16x32_bf16 v[238:241], v[242:245], v[44:47], v[238:241]
	v_add_u32_e32 v168, s23, v113
	v_add_u32_e32 v169, s22, v114
	v_add_u32_e32 v221, s27, v169
	ds_read_b64_tr_b16 v[52:53], v168
	ds_read_b64_tr_b16 v[54:55], v168 offset:2304
	ds_read_b64_tr_b16 v[192:193], v221
	ds_read_b64_tr_b16 v[194:195], v221 offset:1536
	ds_read_b64_tr_b16 v[196:197], v169 offset:64
	ds_read_b64_tr_b16 v[198:199], v169 offset:1600
	ds_read_b64_tr_b16 v[184:185], v168 offset:4608
	ds_read_b64_tr_b16 v[186:187], v168 offset:6912
	ds_read_b64_tr_b16 v[234:235], v221 offset:3072
	ds_read_b64_tr_b16 v[236:237], v221 offset:4608
	ds_read_b64_tr_b16 v[242:243], v169 offset:3136
	ds_read_b64_tr_b16 v[244:245], v169 offset:4672
	v_cndmask_b32_e64 v48, v48, 0, s[60:61]
	v_cndmask_b32_e64 v49, 0, v49, s[62:63]
	v_cndmask_b32_e64 v50, v50, 0, s[64:65]
	v_cndmask_b32_e64 v51, v51, 0, s[90:91]
	v_cndmask_b32_e64 v180, v180, 0, s[66:67]
	v_cndmask_b32_e64 v181, v181, 0, s[68:69]
	v_cndmask_b32_e64 v182, v182, 0, s[70:71]
	v_cndmask_b32_e64 v183, v183, 0, s[72:73]
	v_cndmask_b32_e64 v188, v188, 0, s[74:75]
	v_cndmask_b32_e64 v189, v189, 0, s[76:77]
	v_cndmask_b32_e64 v190, v190, 0, s[78:79]
	v_cndmask_b32_e64 v191, v191, 0, s[80:81]
	v_cndmask_b32_e64 v36, v36, 0, s[82:83]
	v_cndmask_b32_e64 v37, v37, 0, s[84:85]
	v_cndmask_b32_e64 v38, v38, 0, s[86:87]
	v_cndmask_b32_e64 v39, v39, 0, s[88:89]
	v_cvt_pk_bf16_f32 v40, v48, v49
	v_cvt_pk_bf16_f32 v41, v50, v51
	v_cvt_pk_bf16_f32 v42, v180, v181
	v_cvt_pk_bf16_f32 v43, v182, v183
	v_cvt_pk_bf16_f32 v44, v188, v189
	v_cvt_pk_bf16_f32 v45, v190, v191
	v_cvt_pk_bf16_f32 v46, v36, v37
	v_cvt_pk_bf16_f32 v47, v38, v39
	s_waitcnt lgkmcnt(13)
	v_max_f32_e32 v0, v0, v0
	s_waitcnt lgkmcnt(12)
	v_mfma_f32_16x16x32_bf16 v[200:203], v[200:203], v[40:43], 0
	v_mfma_f32_16x16x32_bf16 v[204:207], v[204:207], v[40:43], 0
	v_mfma_f32_16x16x32_bf16 v[200:203], v[246:249], v[44:47], v[200:203]
	v_mfma_f32_16x16x32_bf16 v[204:207], v[216:219], v[44:47], v[204:207]
	v_pk_mul_f32 v[26:27], v[26:27], v[176:177] op_sel_hi:[1,0]
	v_pk_mul_f32 v[24:25], v[24:25], v[176:177] op_sel_hi:[1,0]
	v_mul_f32_e64 v18, v18, v176
	v_mul_f32_e64 v19, v19, v176
	v_pk_mul_f32 v[16:17], v[16:17], v[176:177] op_sel_hi:[1,0]
	v_mov_b32_e32 v250, v3
	s_waitcnt lgkmcnt(8)
	v_mfma_f32_16x16x32_bf16 v[24:27], v[192:195], v[52:55], v[24:27]
	s_waitcnt lgkmcnt(6)
	v_mfma_f32_16x16x32_bf16 v[16:19], v[196:199], v[52:55], v[16:19]
	s_waitcnt lgkmcnt(2)
	v_mfma_f32_16x16x32_bf16 v[24:27], v[234:237], v[184:187], v[24:27]
	s_waitcnt lgkmcnt(0)
	v_mfma_f32_16x16x32_bf16 v[16:19], v[242:245], v[184:187], v[16:19]
	v_pk_mul_f32 v[48:49], v[2:3], v[200:201] op_sel_hi:[0,1]
	v_pk_fma_f32 v[48:49], v[250:251], v[230:231], v[48:49] op_sel_hi:[0,1,1]
	v_pk_mul_f32 v[50:51], v[2:3], v[202:203] op_sel_hi:[0,1]
	v_pk_fma_f32 v[50:51], v[250:251], v[232:233], v[50:51] op_sel_hi:[0,1,1]
	v_mul_f32_e32 v2, v2, v204
	v_fma_f32 v2, v250, v238, v2
	ds_bpermute_b32 v2, v139, v2
	v_add3_u32 v168, s34, v115, v129
	v_cvt_pk_bf16_f32 v179, v24, 0
	v_cvt_pk_bf16_f32 v208, v25, 0
	v_cvt_pk_bf16_f32 v209, v26, 0
	v_cvt_pk_bf16_f32 v220, v27, 0
	ds_write_b16 v168, v179
	ds_write_b16 v168, v208 offset:144
	ds_write_b16 v168, v209 offset:288
	ds_write_b16 v168, v220 offset:432
	s_and_b64 vcc, exec, s[36:37]
	s_cbranch_vccnz .Lml_skip_ones
	v_add3_u32 v169, s34, v112, v115
	v_cvt_pk_bf16_f32 v179, v16, 0
	v_cvt_pk_bf16_f32 v208, v17, 0
	v_cvt_pk_bf16_f32 v209, v18, 0
	v_cvt_pk_bf16_f32 v220, v19, 0
	ds_write_b16 v169, v179 offset:4608
	ds_write_b16 v169, v208 offset:4752
	ds_write_b16 v169, v209 offset:4896
	ds_write_b16 v169, v220 offset:5040
